# P7 up-proj epilogue rewritten with packed f32 fma/mul, rstd LDS reads batched; stacks on P4,P5,P8 epilogues
# baseline (speedup 1.0000x reference)
; __device__ __forceinline__ unsigned cvt_pk_bf16(float lo, float hi) { unsigned r; asm volatile("v_cvt_pk_bf16_f32 %0, %1, %2" : "=v"(r) : "v"(lo), "v"(hi)); return r; }
;     __device__ __forceinline__ void operator()(const f32x4 (&acc)[2][2][4][2], const Unit& u, int wr, int wc, int fr, int fq) const {
;         const int row0 = u.pm * BM + wr * 64 + fr, col0 = u.pn * BM + wc * 32 + 8 * fq, b = (u.pm * BM) >> 12;
;         f32x4 cbv[2][2];
; #pragma unroll
;         for (int bj = 0; bj < 2; ++bj)
; #pragma unroll
;             for (int n = 0; n < 2; ++n) cbv[bj][n] = *(const f32x4*)(cb + (size_t)b * 8192 + col0 + bj * HALF + 4 * n);
; #pragma unroll
;         for (int ai = 0; ai < 2; ++ai)
; #pragma unroll
;             for (int m = 0; m < 4; ++m) { const int rl = wr * 64 + fr + ai * HALF + m * 16; bf16_t* rowp = O + (size_t)(u.pm * BM + rl) * ldc + col0;
;                 const float rs = rstd[((u.pm >> 2) & 1) * 256 + rl];
; #pragma unroll
;                 for (int bj = 0; bj < 2; ++bj) { float v[8];
; #pragma unroll
;                     for (int e = 0; e < 8; ++e) { const float x = fmaxf(acc[ai][bj][m][e >> 2][e & 3] * rs + cbv[bj][e >> 2][e & 3], 0.f); v[e] = x * x; }
;                     u32x4 w; w.x = cvt_pk_bf16(v[0], v[1]); w.y = cvt_pk_bf16(v[2], v[3]); w.z = cvt_pk_bf16(v[4], v[5]); w.w = cvt_pk_bf16(v[6], v[7]);
;                     *(u32x4*)(rowp + bj * HALF) = w; } }
;     }
.LBB0_997:
	s_ashr_i32 s24, s22, 4
	s_ashr_i32 s25, s24, 31
	s_lshl_b64 s[24:25], s[24:25], 15
	s_add_u32 s24, s36, s24
	s_addc_u32 s25, s37, s25
	s_lshl_b32 s15, s22, 8
	s_and_b32 s17, s15, 0x400
	v_lshl_or_b32 v160, s42, 8, v171
	v_lshlrev_b32_e32 v161, 2, v160
	global_load_dwordx4 v[128:131], v161, s[24:25]
	global_load_dwordx4 v[132:135], v161, s[24:25] offset:16
	global_load_dwordx4 v[136:139], v161, s[24:25] offset:512
	global_load_dwordx4 v[140:143], v161, s[24:25] offset:528
	v_add_u32_e32 v161, s17, v172
	ds_read_b32 v176, v161
	ds_read_b32 v177, v161 offset:64
	ds_read_b32 v178, v161 offset:128
	ds_read_b32 v179, v161 offset:192
	ds_read_b32 v180, v161 offset:512
	ds_read_b32 v181, v161 offset:576
	ds_read_b32 v182, v161 offset:640
	ds_read_b32 v183, v161 offset:704
	v_add_u32_e32 v161, s15, v162
	v_lshlrev_b32_e32 v160, 1, v160
	v_lshl_add_u32 v160, v161, 14, v160
	s_waitcnt vmcnt(0) lgkmcnt(0)
	v_pk_fma_f32 v[124:125], v[124:125], v[176:177], v[128:129] op_sel_hi:[1,0,1]
	v_pk_fma_f32 v[126:127], v[126:127], v[176:177], v[130:131] op_sel_hi:[1,0,1]
	v_pk_fma_f32 v[120:121], v[120:121], v[176:177], v[132:133] op_sel_hi:[1,0,1]
	v_pk_fma_f32 v[122:123], v[122:123], v[176:177], v[134:135] op_sel_hi:[1,0,1]
	v_max_f32_e32 v188, 0, v124
	v_max_f32_e32 v189, 0, v125
	v_max_f32_e32 v190, 0, v126
	v_max_f32_e32 v191, 0, v127
	v_max_f32_e32 v192, 0, v120
	v_max_f32_e32 v193, 0, v121
	v_max_f32_e32 v194, 0, v122
	v_max_f32_e32 v195, 0, v123
	v_pk_mul_f32 v[124:125], v[188:189], v[188:189]
	v_pk_mul_f32 v[126:127], v[190:191], v[190:191]
	v_pk_mul_f32 v[120:121], v[192:193], v[192:193]
	v_pk_mul_f32 v[122:123], v[194:195], v[194:195]
	v_cvt_pk_bf16_f32 v188, v124, v125
	v_cvt_pk_bf16_f32 v189, v126, v127
	v_cvt_pk_bf16_f32 v190, v120, v121
	v_cvt_pk_bf16_f32 v191, v122, v123
	global_store_dwordx4 v160, v[188:191], s[72:73]
	v_pk_fma_f32 v[116:117], v[116:117], v[176:177], v[136:137] op_sel_hi:[1,0,1]
	v_pk_fma_f32 v[118:119], v[118:119], v[176:177], v[138:139] op_sel_hi:[1,0,1]
	v_pk_fma_f32 v[112:113], v[112:113], v[176:177], v[140:141] op_sel_hi:[1,0,1]
	v_pk_fma_f32 v[114:115], v[114:115], v[176:177], v[142:143] op_sel_hi:[1,0,1]
	v_max_f32_e32 v196, 0, v116
	v_max_f32_e32 v197, 0, v117
	v_max_f32_e32 v198, 0, v118
	v_max_f32_e32 v199, 0, v119
	v_max_f32_e32 v200, 0, v112
	v_max_f32_e32 v201, 0, v113
	v_max_f32_e32 v202, 0, v114
	v_max_f32_e32 v203, 0, v115
	v_pk_mul_f32 v[116:117], v[196:197], v[196:197]
	v_pk_mul_f32 v[118:119], v[198:199], v[198:199]
	v_pk_mul_f32 v[112:113], v[200:201], v[200:201]
	v_pk_mul_f32 v[114:115], v[202:203], v[202:203]
	v_cvt_pk_bf16_f32 v196, v116, v117
	v_cvt_pk_bf16_f32 v197, v118, v119
	v_cvt_pk_bf16_f32 v198, v112, v113
	v_cvt_pk_bf16_f32 v199, v114, v115
	global_store_dwordx4 v160, v[196:199], s[72:73] offset:256
	v_add_u32_e32 v160, 0x40000, v160
	v_pk_fma_f32 v[108:109], v[108:109], v[176:177], v[128:129] op_sel:[0,1,0] op_sel_hi:[1,1,1]
	v_pk_fma_f32 v[110:111], v[110:111], v[176:177], v[130:131] op_sel:[0,1,0] op_sel_hi:[1,1,1]
	v_pk_fma_f32 v[104:105], v[104:105], v[176:177], v[132:133] op_sel:[0,1,0] op_sel_hi:[1,1,1]
	v_pk_fma_f32 v[106:107], v[106:107], v[176:177], v[134:135] op_sel:[0,1,0] op_sel_hi:[1,1,1]
	v_max_f32_e32 v188, 0, v108
	v_max_f32_e32 v189, 0, v109
	v_max_f32_e32 v190, 0, v110
	v_max_f32_e32 v191, 0, v111
	v_max_f32_e32 v192, 0, v104
	v_max_f32_e32 v193, 0, v105
	v_max_f32_e32 v194, 0, v106
	v_max_f32_e32 v195, 0, v107
	v_pk_mul_f32 v[108:109], v[188:189], v[188:189]
	v_pk_mul_f32 v[110:111], v[190:191], v[190:191]
	v_pk_mul_f32 v[104:105], v[192:193], v[192:193]
	v_pk_mul_f32 v[106:107], v[194:195], v[194:195]
	v_cvt_pk_bf16_f32 v188, v108, v109
	v_cvt_pk_bf16_f32 v189, v110, v111
	v_cvt_pk_bf16_f32 v190, v104, v105
	v_cvt_pk_bf16_f32 v191, v106, v107
	global_store_dwordx4 v160, v[188:191], s[72:73]
	v_pk_fma_f32 v[100:101], v[100:101], v[176:177], v[136:137] op_sel:[0,1,0] op_sel_hi:[1,1,1]
	v_pk_fma_f32 v[102:103], v[102:103], v[176:177], v[138:139] op_sel:[0,1,0] op_sel_hi:[1,1,1]
	v_pk_fma_f32 v[96:97], v[96:97], v[176:177], v[140:141] op_sel:[0,1,0] op_sel_hi:[1,1,1]
	v_pk_fma_f32 v[98:99], v[98:99], v[176:177], v[142:143] op_sel:[0,1,0] op_sel_hi:[1,1,1]
	v_max_f32_e32 v196, 0, v100
	v_max_f32_e32 v197, 0, v101
	v_max_f32_e32 v198, 0, v102
	v_max_f32_e32 v199, 0, v103
	v_max_f32_e32 v200, 0, v96
	v_max_f32_e32 v201, 0, v97
	v_max_f32_e32 v202, 0, v98
	v_max_f32_e32 v203, 0, v99
	v_pk_mul_f32 v[100:101], v[196:197], v[196:197]
	v_pk_mul_f32 v[102:103], v[198:199], v[198:199]
	v_pk_mul_f32 v[96:97], v[200:201], v[200:201]
	v_pk_mul_f32 v[98:99], v[202:203], v[202:203]
	v_cvt_pk_bf16_f32 v196, v100, v101
	v_cvt_pk_bf16_f32 v197, v102, v103
	v_cvt_pk_bf16_f32 v198, v96, v97
	v_cvt_pk_bf16_f32 v199, v98, v99
	global_store_dwordx4 v160, v[196:199], s[72:73] offset:256
	v_add_u32_e32 v160, 0x40000, v160
	v_pk_fma_f32 v[92:93], v[92:93], v[178:179], v[128:129] op_sel_hi:[1,0,1]
	v_pk_fma_f32 v[94:95], v[94:95], v[178:179], v[130:131] op_sel_hi:[1,0,1]
	v_pk_fma_f32 v[88:89], v[88:89], v[178:179], v[132:133] op_sel_hi:[1,0,1]
	v_pk_fma_f32 v[90:91], v[90:91], v[178:179], v[134:135] op_sel_hi:[1,0,1]
	v_max_f32_e32 v188, 0, v92
	v_max_f32_e32 v189, 0, v93
	v_max_f32_e32 v190, 0, v94
	v_max_f32_e32 v191, 0, v95
	v_max_f32_e32 v192, 0, v88
	v_max_f32_e32 v193, 0, v89
	v_max_f32_e32 v194, 0, v90
	v_max_f32_e32 v195, 0, v91
	v_pk_mul_f32 v[92:93], v[188:189], v[188:189]
	v_pk_mul_f32 v[94:95], v[190:191], v[190:191]
	v_pk_mul_f32 v[88:89], v[192:193], v[192:193]
	v_pk_mul_f32 v[90:91], v[194:195], v[194:195]
	v_cvt_pk_bf16_f32 v188, v92, v93
	v_cvt_pk_bf16_f32 v189, v94, v95
; __device__ __forceinline__ unsigned cvt_pk_bf16(float lo, float hi) { unsigned r; asm volatile("v_cvt_pk_bf16_f32 %0, %1, %2" : "=v"(r) : "v"(lo), "v"(hi)); return r; }
;     __device__ __forceinline__ void operator()(const f32x4 (&acc)[2][2][4][2], const Unit& u, int wr, int wc, int fr, int fq) const {
;     ...
;             for (int m = 0; m < 4; ++m) { const int rl = wr * 64 + fr + ai * HALF + m * 16; bf16_t* rowp = O + (size_t)(u.pm * BM + rl) * ldc + col0;
;                 const float rs = rstd[((u.pm >> 2) & 1) * 256 + rl];
; #pragma unroll
;                 for (int bj = 0; bj < 2; ++bj) { float v[8];
; #pragma unroll
;                     for (int e = 0; e < 8; ++e) { const float x = fmaxf(acc[ai][bj][m][e >> 2][e & 3] * rs + cbv[bj][e >> 2][e & 3], 0.f); v[e] = x * x; }
;                     u32x4 w; w.x = cvt_pk_bf16(v[0], v[1]); w.y = cvt_pk_bf16(v[2], v[3]); w.z = cvt_pk_bf16(v[4], v[5]); w.w = cvt_pk_bf16(v[6], v[7]);
;                     *(u32x4*)(rowp + bj * HALF) = w; } }
	v_cvt_pk_bf16_f32 v190, v88, v89
	v_cvt_pk_bf16_f32 v191, v90, v91
	global_store_dwordx4 v160, v[188:191], s[72:73]
	v_pk_fma_f32 v[84:85], v[84:85], v[178:179], v[136:137] op_sel_hi:[1,0,1]
	v_pk_fma_f32 v[86:87], v[86:87], v[178:179], v[138:139] op_sel_hi:[1,0,1]
	v_pk_fma_f32 v[80:81], v[80:81], v[178:179], v[140:141] op_sel_hi:[1,0,1]
	v_pk_fma_f32 v[82:83], v[82:83], v[178:179], v[142:143] op_sel_hi:[1,0,1]
	v_max_f32_e32 v196, 0, v84
	v_max_f32_e32 v197, 0, v85
	v_max_f32_e32 v198, 0, v86
	v_max_f32_e32 v199, 0, v87
	v_max_f32_e32 v200, 0, v80
	v_max_f32_e32 v201, 0, v81
	v_max_f32_e32 v202, 0, v82
	v_max_f32_e32 v203, 0, v83
	v_pk_mul_f32 v[84:85], v[196:197], v[196:197]
	v_pk_mul_f32 v[86:87], v[198:199], v[198:199]
	v_pk_mul_f32 v[80:81], v[200:201], v[200:201]
	v_pk_mul_f32 v[82:83], v[202:203], v[202:203]
	v_cvt_pk_bf16_f32 v196, v84, v85
	v_cvt_pk_bf16_f32 v197, v86, v87
	v_cvt_pk_bf16_f32 v198, v80, v81
	v_cvt_pk_bf16_f32 v199, v82, v83
	global_store_dwordx4 v160, v[196:199], s[72:73] offset:256
	v_add_u32_e32 v160, 0x40000, v160
	v_pk_fma_f32 v[76:77], v[76:77], v[178:179], v[128:129] op_sel:[0,1,0] op_sel_hi:[1,1,1]
	v_pk_fma_f32 v[78:79], v[78:79], v[178:179], v[130:131] op_sel:[0,1,0] op_sel_hi:[1,1,1]
	v_pk_fma_f32 v[72:73], v[72:73], v[178:179], v[132:133] op_sel:[0,1,0] op_sel_hi:[1,1,1]
	v_pk_fma_f32 v[74:75], v[74:75], v[178:179], v[134:135] op_sel:[0,1,0] op_sel_hi:[1,1,1]
	v_max_f32_e32 v188, 0, v76
	v_max_f32_e32 v189, 0, v77
	v_max_f32_e32 v190, 0, v78
	v_max_f32_e32 v191, 0, v79
	v_max_f32_e32 v192, 0, v72
	v_max_f32_e32 v193, 0, v73
	v_max_f32_e32 v194, 0, v74
	v_max_f32_e32 v195, 0, v75
	v_pk_mul_f32 v[76:77], v[188:189], v[188:189]
	v_pk_mul_f32 v[78:79], v[190:191], v[190:191]
	v_pk_mul_f32 v[72:73], v[192:193], v[192:193]
	v_pk_mul_f32 v[74:75], v[194:195], v[194:195]
	v_cvt_pk_bf16_f32 v188, v76, v77
	v_cvt_pk_bf16_f32 v189, v78, v79
	v_cvt_pk_bf16_f32 v190, v72, v73
	v_cvt_pk_bf16_f32 v191, v74, v75
	global_store_dwordx4 v160, v[188:191], s[72:73]
	v_pk_fma_f32 v[68:69], v[68:69], v[178:179], v[136:137] op_sel:[0,1,0] op_sel_hi:[1,1,1]
	v_pk_fma_f32 v[70:71], v[70:71], v[178:179], v[138:139] op_sel:[0,1,0] op_sel_hi:[1,1,1]
	v_pk_fma_f32 v[64:65], v[64:65], v[178:179], v[140:141] op_sel:[0,1,0] op_sel_hi:[1,1,1]
	v_pk_fma_f32 v[66:67], v[66:67], v[178:179], v[142:143] op_sel:[0,1,0] op_sel_hi:[1,1,1]
	v_max_f32_e32 v196, 0, v68
	v_max_f32_e32 v197, 0, v69
	v_max_f32_e32 v198, 0, v70
	v_max_f32_e32 v199, 0, v71
	v_max_f32_e32 v200, 0, v64
	v_max_f32_e32 v201, 0, v65
	v_max_f32_e32 v202, 0, v66
	v_max_f32_e32 v203, 0, v67
	v_pk_mul_f32 v[68:69], v[196:197], v[196:197]
	v_pk_mul_f32 v[70:71], v[198:199], v[198:199]
	v_pk_mul_f32 v[64:65], v[200:201], v[200:201]
	v_pk_mul_f32 v[66:67], v[202:203], v[202:203]
	v_cvt_pk_bf16_f32 v196, v68, v69
	v_cvt_pk_bf16_f32 v197, v70, v71
	v_cvt_pk_bf16_f32 v198, v64, v65
	v_cvt_pk_bf16_f32 v199, v66, v67
	global_store_dwordx4 v160, v[196:199], s[72:73] offset:256
	v_add_u32_e32 v160, 0x140000, v160
	v_pk_fma_f32 v[60:61], v[60:61], v[180:181], v[128:129] op_sel_hi:[1,0,1]
	v_pk_fma_f32 v[62:63], v[62:63], v[180:181], v[130:131] op_sel_hi:[1,0,1]
	v_pk_fma_f32 v[56:57], v[56:57], v[180:181], v[132:133] op_sel_hi:[1,0,1]
	v_pk_fma_f32 v[58:59], v[58:59], v[180:181], v[134:135] op_sel_hi:[1,0,1]
	v_max_f32_e32 v188, 0, v60
	v_max_f32_e32 v189, 0, v61
	v_max_f32_e32 v190, 0, v62
	v_max_f32_e32 v191, 0, v63
	v_max_f32_e32 v192, 0, v56
	v_max_f32_e32 v193, 0, v57
	v_max_f32_e32 v194, 0, v58
	v_max_f32_e32 v195, 0, v59
	v_pk_mul_f32 v[60:61], v[188:189], v[188:189]
	v_pk_mul_f32 v[62:63], v[190:191], v[190:191]
	v_pk_mul_f32 v[56:57], v[192:193], v[192:193]
	v_pk_mul_f32 v[58:59], v[194:195], v[194:195]
	v_cvt_pk_bf16_f32 v188, v60, v61
	v_cvt_pk_bf16_f32 v189, v62, v63
	v_cvt_pk_bf16_f32 v190, v56, v57
	v_cvt_pk_bf16_f32 v191, v58, v59
	global_store_dwordx4 v160, v[188:191], s[72:73]
	v_pk_fma_f32 v[52:53], v[52:53], v[180:181], v[136:137] op_sel_hi:[1,0,1]
	v_pk_fma_f32 v[54:55], v[54:55], v[180:181], v[138:139] op_sel_hi:[1,0,1]
	v_pk_fma_f32 v[48:49], v[48:49], v[180:181], v[140:141] op_sel_hi:[1,0,1]
	v_pk_fma_f32 v[50:51], v[50:51], v[180:181], v[142:143] op_sel_hi:[1,0,1]
	v_max_f32_e32 v196, 0, v52
	v_max_f32_e32 v197, 0, v53
	v_max_f32_e32 v198, 0, v54
	v_max_f32_e32 v199, 0, v55
	v_max_f32_e32 v200, 0, v48
	v_max_f32_e32 v201, 0, v49
	v_max_f32_e32 v202, 0, v50
	v_max_f32_e32 v203, 0, v51
	v_pk_mul_f32 v[52:53], v[196:197], v[196:197]
	v_pk_mul_f32 v[54:55], v[198:199], v[198:199]
	v_pk_mul_f32 v[48:49], v[200:201], v[200:201]
	v_pk_mul_f32 v[50:51], v[202:203], v[202:203]
	v_cvt_pk_bf16_f32 v196, v52, v53
	v_cvt_pk_bf16_f32 v197, v54, v55
	v_cvt_pk_bf16_f32 v198, v48, v49
	v_cvt_pk_bf16_f32 v199, v50, v51
	global_store_dwordx4 v160, v[196:199], s[72:73] offset:256
	v_add_u32_e32 v160, 0x40000, v160
	v_pk_fma_f32 v[44:45], v[44:45], v[180:181], v[128:129] op_sel:[0,1,0] op_sel_hi:[1,1,1]
	v_pk_fma_f32 v[46:47], v[46:47], v[180:181], v[130:131] op_sel:[0,1,0] op_sel_hi:[1,1,1]
	v_pk_fma_f32 v[40:41], v[40:41], v[180:181], v[132:133] op_sel:[0,1,0] op_sel_hi:[1,1,1]
	v_pk_fma_f32 v[42:43], v[42:43], v[180:181], v[134:135] op_sel:[0,1,0] op_sel_hi:[1,1,1]
	v_max_f32_e32 v188, 0, v44
	v_max_f32_e32 v189, 0, v45
	v_max_f32_e32 v190, 0, v46
	v_max_f32_e32 v191, 0, v47
	v_max_f32_e32 v192, 0, v40
; __device__ __forceinline__ unsigned cvt_pk_bf16(float lo, float hi) { unsigned r; asm volatile("v_cvt_pk_bf16_f32 %0, %1, %2" : "=v"(r) : "v"(lo), "v"(hi)); return r; }
;     __device__ __forceinline__ void operator()(const f32x4 (&acc)[2][2][4][2], const Unit& u, int wr, int wc, int fr, int fq) const {
;     ...
;             for (int m = 0; m < 4; ++m) { const int rl = wr * 64 + fr + ai * HALF + m * 16; bf16_t* rowp = O + (size_t)(u.pm * BM + rl) * ldc + col0;
;                 const float rs = rstd[((u.pm >> 2) & 1) * 256 + rl];
; #pragma unroll
;                 for (int bj = 0; bj < 2; ++bj) { float v[8];
; #pragma unroll
;                     for (int e = 0; e < 8; ++e) { const float x = fmaxf(acc[ai][bj][m][e >> 2][e & 3] * rs + cbv[bj][e >> 2][e & 3], 0.f); v[e] = x * x; }
;                     u32x4 w; w.x = cvt_pk_bf16(v[0], v[1]); w.y = cvt_pk_bf16(v[2], v[3]); w.z = cvt_pk_bf16(v[4], v[5]); w.w = cvt_pk_bf16(v[6], v[7]);
;                     *(u32x4*)(rowp + bj * HALF) = w; } }
	v_max_f32_e32 v193, 0, v41
	v_max_f32_e32 v194, 0, v42
	v_max_f32_e32 v195, 0, v43
	v_pk_mul_f32 v[44:45], v[188:189], v[188:189]
	v_pk_mul_f32 v[46:47], v[190:191], v[190:191]
	v_pk_mul_f32 v[40:41], v[192:193], v[192:193]
	v_pk_mul_f32 v[42:43], v[194:195], v[194:195]
	v_cvt_pk_bf16_f32 v188, v44, v45
	v_cvt_pk_bf16_f32 v189, v46, v47
	v_cvt_pk_bf16_f32 v190, v40, v41
	v_cvt_pk_bf16_f32 v191, v42, v43
	global_store_dwordx4 v160, v[188:191], s[72:73]
	v_pk_fma_f32 v[36:37], v[36:37], v[180:181], v[136:137] op_sel:[0,1,0] op_sel_hi:[1,1,1]
	v_pk_fma_f32 v[38:39], v[38:39], v[180:181], v[138:139] op_sel:[0,1,0] op_sel_hi:[1,1,1]
	v_pk_fma_f32 v[32:33], v[32:33], v[180:181], v[140:141] op_sel:[0,1,0] op_sel_hi:[1,1,1]
	v_pk_fma_f32 v[34:35], v[34:35], v[180:181], v[142:143] op_sel:[0,1,0] op_sel_hi:[1,1,1]
	v_max_f32_e32 v196, 0, v36
	v_max_f32_e32 v197, 0, v37
	v_max_f32_e32 v198, 0, v38
	v_max_f32_e32 v199, 0, v39
	v_max_f32_e32 v200, 0, v32
	v_max_f32_e32 v201, 0, v33
	v_max_f32_e32 v202, 0, v34
	v_max_f32_e32 v203, 0, v35
	v_pk_mul_f32 v[36:37], v[196:197], v[196:197]
	v_pk_mul_f32 v[38:39], v[198:199], v[198:199]
	v_pk_mul_f32 v[32:33], v[200:201], v[200:201]
	v_pk_mul_f32 v[34:35], v[202:203], v[202:203]
	v_cvt_pk_bf16_f32 v196, v36, v37
	v_cvt_pk_bf16_f32 v197, v38, v39
	v_cvt_pk_bf16_f32 v198, v32, v33
	v_cvt_pk_bf16_f32 v199, v34, v35
	global_store_dwordx4 v160, v[196:199], s[72:73] offset:256
	v_add_u32_e32 v160, 0x40000, v160
	v_pk_fma_f32 v[28:29], v[28:29], v[182:183], v[128:129] op_sel_hi:[1,0,1]
	v_pk_fma_f32 v[30:31], v[30:31], v[182:183], v[130:131] op_sel_hi:[1,0,1]
	v_pk_fma_f32 v[24:25], v[24:25], v[182:183], v[132:133] op_sel_hi:[1,0,1]
	v_pk_fma_f32 v[26:27], v[26:27], v[182:183], v[134:135] op_sel_hi:[1,0,1]
	v_max_f32_e32 v188, 0, v28
	v_max_f32_e32 v189, 0, v29
	v_max_f32_e32 v190, 0, v30
	v_max_f32_e32 v191, 0, v31
	v_max_f32_e32 v192, 0, v24
	v_max_f32_e32 v193, 0, v25
	v_max_f32_e32 v194, 0, v26
	v_max_f32_e32 v195, 0, v27
	v_pk_mul_f32 v[28:29], v[188:189], v[188:189]
	v_pk_mul_f32 v[30:31], v[190:191], v[190:191]
	v_pk_mul_f32 v[24:25], v[192:193], v[192:193]
	v_pk_mul_f32 v[26:27], v[194:195], v[194:195]
	v_cvt_pk_bf16_f32 v188, v28, v29
	v_cvt_pk_bf16_f32 v189, v30, v31
	v_cvt_pk_bf16_f32 v190, v24, v25
	v_cvt_pk_bf16_f32 v191, v26, v27
	global_store_dwordx4 v160, v[188:191], s[72:73]
	v_pk_fma_f32 v[20:21], v[20:21], v[182:183], v[136:137] op_sel_hi:[1,0,1]
	v_pk_fma_f32 v[22:23], v[22:23], v[182:183], v[138:139] op_sel_hi:[1,0,1]
	v_pk_fma_f32 v[16:17], v[16:17], v[182:183], v[140:141] op_sel_hi:[1,0,1]
	v_pk_fma_f32 v[18:19], v[18:19], v[182:183], v[142:143] op_sel_hi:[1,0,1]
	v_max_f32_e32 v196, 0, v20
	v_max_f32_e32 v197, 0, v21
	v_max_f32_e32 v198, 0, v22
	v_max_f32_e32 v199, 0, v23
	v_max_f32_e32 v200, 0, v16
	v_max_f32_e32 v201, 0, v17
	v_max_f32_e32 v202, 0, v18
	v_max_f32_e32 v203, 0, v19
	v_pk_mul_f32 v[20:21], v[196:197], v[196:197]
	v_pk_mul_f32 v[22:23], v[198:199], v[198:199]
	v_pk_mul_f32 v[16:17], v[200:201], v[200:201]
	v_pk_mul_f32 v[18:19], v[202:203], v[202:203]
	v_cvt_pk_bf16_f32 v196, v20, v21
	v_cvt_pk_bf16_f32 v197, v22, v23
	v_cvt_pk_bf16_f32 v198, v16, v17
	v_cvt_pk_bf16_f32 v199, v18, v19
	global_store_dwordx4 v160, v[196:199], s[72:73] offset:256
	v_add_u32_e32 v160, 0x40000, v160
	v_pk_fma_f32 v[12:13], v[12:13], v[182:183], v[128:129] op_sel:[0,1,0] op_sel_hi:[1,1,1]
	v_pk_fma_f32 v[14:15], v[14:15], v[182:183], v[130:131] op_sel:[0,1,0] op_sel_hi:[1,1,1]
	v_pk_fma_f32 v[8:9], v[8:9], v[182:183], v[132:133] op_sel:[0,1,0] op_sel_hi:[1,1,1]
	v_pk_fma_f32 v[10:11], v[10:11], v[182:183], v[134:135] op_sel:[0,1,0] op_sel_hi:[1,1,1]
	v_max_f32_e32 v188, 0, v12
	v_max_f32_e32 v189, 0, v13
	v_max_f32_e32 v190, 0, v14
	v_max_f32_e32 v191, 0, v15
	v_max_f32_e32 v192, 0, v8
	v_max_f32_e32 v193, 0, v9
	v_max_f32_e32 v194, 0, v10
	v_max_f32_e32 v195, 0, v11
	v_pk_mul_f32 v[12:13], v[188:189], v[188:189]
	v_pk_mul_f32 v[14:15], v[190:191], v[190:191]
	v_pk_mul_f32 v[8:9], v[192:193], v[192:193]
	v_pk_mul_f32 v[10:11], v[194:195], v[194:195]
	v_cvt_pk_bf16_f32 v188, v12, v13
	v_cvt_pk_bf16_f32 v189, v14, v15
	v_cvt_pk_bf16_f32 v190, v8, v9
	v_cvt_pk_bf16_f32 v191, v10, v11
	global_store_dwordx4 v160, v[188:191], s[72:73]
	v_pk_fma_f32 v[4:5], v[4:5], v[182:183], v[136:137] op_sel:[0,1,0] op_sel_hi:[1,1,1]
	v_pk_fma_f32 v[6:7], v[6:7], v[182:183], v[138:139] op_sel:[0,1,0] op_sel_hi:[1,1,1]
	v_pk_fma_f32 v[0:1], v[0:1], v[182:183], v[140:141] op_sel:[0,1,0] op_sel_hi:[1,1,1]
	v_pk_fma_f32 v[2:3], v[2:3], v[182:183], v[142:143] op_sel:[0,1,0] op_sel_hi:[1,1,1]
	v_max_f32_e32 v196, 0, v4
	v_max_f32_e32 v197, 0, v5
	v_max_f32_e32 v198, 0, v6
	v_max_f32_e32 v199, 0, v7
	v_max_f32_e32 v200, 0, v0
	v_max_f32_e32 v201, 0, v1
	v_max_f32_e32 v202, 0, v2
	v_max_f32_e32 v203, 0, v3
	v_pk_mul_f32 v[4:5], v[196:197], v[196:197]
	v_pk_mul_f32 v[6:7], v[198:199], v[198:199]
	v_pk_mul_f32 v[0:1], v[200:201], v[200:201]
	v_pk_mul_f32 v[2:3], v[202:203], v[202:203]
	v_cvt_pk_bf16_f32 v196, v4, v5
	v_cvt_pk_bf16_f32 v197, v6, v7
	v_cvt_pk_bf16_f32 v198, v0, v1
	v_cvt_pk_bf16_f32 v199, v2, v3
	global_store_dwordx4 v160, v[196:199], s[72:73] offset:256
	s_andn2_b64 vcc, exec, s[4:5]
	s_mov_b64 s[4:5], -1
	s_cbranch_vccnz .LBB0_986
	s_andn2_b64 vcc, exec, s[6:7]
	s_cbranch_vccnz .LBB0_985
	s_barrier
	s_branch .LBB0_985
